# PH2 transpose map rotated off the sample-pool workgroups; PH8 sample-norm g_fin loads hoisted; EpiUp conv weights + row sums staged by LDS-DMA during the last k-step
# speedup vs baseline: 1.1126x; 1.0023x over previous
; #define LAS __attribute__((address_space(3)))
; __global__ void __launch_bounds__(512, 2) fwd_kernel(Args a) {
;     ...
;             const float* g_ffn = KIN(20); const float* w_up = KIN(21); bf16* WUP = WSP(bf16, WS_WUP);
;             LAS float* scr = (LAS float*)(lds + wave * 16384);
;             for (int r = gw; r < 16 * 176; r += NGW) { const int kb = r / 176, nb = r % 176; const int n0 = 32 * nb, pn = n0 >> 8, lr = n0 & 255; const int src = lr < 128 ? 128 * pn + lr : FF + 128 * pn + (lr - 128);
;                 transpose_item(w_up, FF2, WUP, D, 64 * kb, n0, src, g_ffn, scr, lane); }
.LBB0_339:
	s_or_b64 exec, exec, s[8:9]
	s_add_i32 s96, s78, 0x300
	s_sub_i32 s97, s96, s30
	s_cmp_ge_u32 s96, s30
	s_cselect_b32 s96, s97, s96
	s_cmpk_gt_i32 s96, 0xaff
	s_cbranch_scc1 .LBB0_344
	s_load_dwordx4 s[12:15], s[18:19], 0xa0
	v_and_b32_e32 v0, 31, v152
	v_mov_b32_e32 v3, 0
	v_lshlrev_b32_e32 v2, 2, v0
	v_add_u32_e32 v4, s70, v2
	s_waitcnt lgkmcnt(0)
	v_lshl_add_u64 v[0:1], s[14:15], 0, v[2:3]
	v_lshlrev_b32_e32 v2, 3, v152
	s_cmp_lg_u64 s[12:13], 0
	v_lshrrev_b32_e32 v39, 3, v154
	v_and_b32_e32 v2, 56, v2
	v_lshrrev_b32_e32 v38, 5, v154
	s_cselect_b64 s[8:9], -1, 0
	v_mul_u32_u24_e32 v6, 0x84, v2
	v_lshlrev_b32_e32 v2, 1, v2
	v_lshlrev_b32_e32 v7, 2, v39
	v_mul_u32_u24_e32 v5, 0x84, v38
	v_lshl_add_u64 v[2:3], s[16:17], 0, v[2:3]
	s_mov_b64 s[0:1], 0x480000
	v_add3_u32 v40, s70, v6, v7
	v_cndmask_b32_e64 v6, 0, 1, s[8:9]
	v_lshl_add_u64 v[2:3], v[2:3], 0, s[0:1]
	s_lshl_b32 s0, s96, 5
	s_lshl_b32 s1, s30, 5
	s_lshl_b32 s4, s96, 4
	s_lshl_b32 s5, s30, 4
	s_movk_i32 s6, 0x5800
	v_cmp_ne_u32_e64 s[8:9], 1, v6
	v_add_u32_e32 v41, v4, v5
	s_mov_b32 s7, s96
	s_branch .LBB0_342

; #define PG8_STAGE(bufoff, gbase, voff) do { _Pragma("unroll") for (int _i = 0; _i < 2; ++_i) \
;         __builtin_amdgcn_global_load_lds((const unsigned*)((const char*)(gbase) + (voff)[_i]), (PG8_LAS unsigned*)(lds + (bufoff) + ldsw + _i * 8192), 16, 0, 0); } while (0)
; #define PG8_LDA(dst, b, h) do { _Pragma("unroll") for (int m = 0; m < 4; ++m) _Pragma("unroll") for (int k = 0; k < 2; ++k) dst[m][k] = *(const PG8_LAS bf16x8*)(lds + PG8_SA(b, h) + aoff + m * 2048 + k * 1024); } while (0)
; #define PG8_MMA(ai, bj, At, Bt) do { __builtin_amdgcn_s_setprio(1); _Pragma("unroll") for (int m = 0; m < 4; ++m) _Pragma("unroll") for (int n = 0; n < 2; ++n) _Pragma("unroll") for (int k = 0; k < 2; ++k) \
;         acc[ai][bj][m][n] = __builtin_amdgcn_mfma_f32_16x16x32_bf16(Bt[n][k], At[m][k], acc[ai][bj][m][n], 0, 0, 0); __builtin_amdgcn_s_setprio(0); } while (0)
; #define PG8_WAIT_V(n) asm volatile("s_waitcnt vmcnt(" #n ")" ::: "memory")
; #define PG8_WAIT_L(n) asm volatile("s_waitcnt lgkmcnt(" #n ")" ::: "memory")
; #define PG8_BAR __builtin_amdgcn_s_barrier()
; #define PG8_SCHED __builtin_amdgcn_sched_barrier(0)
;     ...
;             PG8_LDA(At, 1, 1); PG8_STAGE(PG8_SB(1, 0), b3, voffB); PG8_STAGE(PG8_SB(1, 1), b3 + hstepB, voffB); PG8_STAGE(PG8_SA(1, 0), a3, voffA);
;             PG8_WAIT_V(8); PG8_WAIT_L(0); PG8_BAR; PG8_MMA(1, 0, At, B0); PG8_MMA(1, 1, At, B1); PG8_BAR; PG8_SCHED;
;     __device__ __forceinline__ void operator()(const f32x4 (&acc)[2][2][4][2], const Unit& u, int wr, int wc, int fr, int fq) const {
;     ...
;             float rs[4];
; #pragma unroll
;             for (int m = 0; m < 4; ++m) rs[m] = rsqrtf(SS[rowb + 16 * m + fr] * (1.0f / D) + EPS);
; #pragma unroll
;             for (int n = 0; n < 2; ++n) {
;                 f32x4 cg[4];
; #pragma unroll
;                 for (int bj = 0; bj < 2; ++bj) {
;                     const int oc = (bj ? FF : 0) + 128 * u.pn + 32 * wc + 8 * fq + 4 * n;
;                     const int cgc = 256 * u.pn + 128 * bj + 32 * wc + 8 * fq + 4 * n;
;                     const f32x4 cw0 = *(const f32x4*)(convw + oc), cw1 = *(const f32x4*)(convw + FF2 + oc), cw2 = *(const f32x4*)(convw + 2 * FF2 + oc), cb = *(const f32x4*)(convb + oc);
.LBB0_867:
	s_cmp_eq_u32 s48, 14
	s_cbranch_scc0 .Lwl_skip
	v_readlane_b32 s56, v236, 19
	v_readfirstlane_b32 s57, v215
	v_and_b32_e32 v226, 31, v215
	v_lshl_add_u32 v226, v226, 1, v153
	s_nop 3
	s_cmp_eq_u32 s56, 0
	s_cbranch_scc0 .Lwl_ss
	v_and_b32_e32 v227, 31, v226
	v_lshlrev_b32_e32 v227, 4, v227
	v_lshrrev_b32_e32 v226, 5, v226
	v_mul_u32_u24_e32 v226, 0x2c00, v226
	v_add_u32_e32 v226, v226, v227
	s_lshl_b32 s96, s12, 9
	v_add_u32_e32 v226, s96, v226
	s_mov_b64 s[94:95], s[16:17]
	s_cmp_eq_u32 s57, 32
	s_cselect_b32 s94, s58, s94
	s_cselect_b32 s95, s59, s95
	s_cmp_eq_u32 s57, 64
	s_cselect_b32 s94, s60, s94
	s_cselect_b32 s95, s61, s95
	s_cmp_eq_u32 s57, 0x60
	s_cselect_b32 s94, s18, s94
	s_cselect_b32 s95, s19, s95
	s_lshl_b32 s57, s57, 5
	s_add_i32 m0, s57, 0x21000
	s_nop 0
	global_load_lds_dwordx4 v226, s[94:95]
	s_branch .Lwl_skip
.Lwl_ss:
	s_cmp_eq_u32 s57, 0
	s_cbranch_scc0 .Lwl_skip
	v_lshlrev_b32_e32 v226, 4, v226
	s_lshl_b32 s96, s88, 10
	v_add_u32_e32 v226, s96, v226
	s_mov_b32 m0, 0x22000
	s_nop 0
	global_load_lds_dwordx4 v226, s[42:43]

;     __device__ __forceinline__ void operator()(const f32x4 (&acc)[2][2][4][2], const Unit& u, int wr, int wc, int fr, int fq) const {
;     ...
;             const int rowb = u.pm * 256 + ai * 128 + wr * 64;
;             const int blk = 4 * u.pm + 2 * ai + wr;
;             float rs[4];
; #pragma unroll
;             for (int m = 0; m < 4; ++m) rs[m] = rsqrtf(SS[rowb + 16 * m + fr] * (1.0f / D) + EPS);
; #pragma unroll
;             for (int n = 0; n < 2; ++n) {
;                 f32x4 cg[4];
; #pragma unroll
;                 for (int bj = 0; bj < 2; ++bj) {
;                     const int oc = (bj ? FF : 0) + 128 * u.pn + 32 * wc + 8 * fq + 4 * n;
;                     const int cgc = 256 * u.pn + 128 * bj + 32 * wc + 8 * fq + 4 * n;
;                     const f32x4 cw0 = *(const f32x4*)(convw + oc), cw1 = *(const f32x4*)(convw + FF2 + oc), cw2 = *(const f32x4*)(convw + 2 * FF2 + oc), cb = *(const f32x4*)(convb + oc);
;                     f32x4 v[4];
; #pragma unroll
;                     for (int m = 0; m < 4; ++m) v[m] = acc[ai][bj][m][n] * rs[m];
.Lfe_begin:
	v_readlane_b32 s13, v236, 19
	s_lshl_b32 s77, s88, 8
	s_lshl_b32 s89, s12, 7
	s_lshl_b32 s75, s88, 2
	s_add_i32 s75, s75, s73
	s_add_i32 s77, s77, s13
	v_add_u32_e32 v246, s77, v153
	v_add_u32_e32 v247, s13, v153
	v_lshlrev_b32_e32 v247, 2, v247
	v_add_u32_e32 v247, 0x22000, v247
	ds_read2_b32 v[238:239], v247 offset0:0 offset1:16
	ds_read2_b32 v[240:241], v247 offset0:32 offset1:48
	ds_read2_b32 v[242:243], v247 offset0:128 offset1:144
	ds_read2_b32 v[244:245], v247 offset0:160 offset1:176
	v_lshlrev_b32_e32 v249, 2, v215
	v_add_u32_e32 v249, 0x21000, v249
	v_add_u32_e32 v248, s89, v215
	v_lshlrev_b32_e32 v237, 2, v248
	v_add_u32_e32 v250, 0x2c00, v237
	ds_read_b128 v[170:173], v249
	ds_read_b128 v[174:177], v249 offset:16
	ds_read_b128 v[178:181], v249 offset:512
	ds_read_b128 v[182:185], v249 offset:528
	ds_read_b128 v[186:189], v249 offset:1024
	ds_read_b128 v[190:193], v249 offset:1040
	ds_read_b128 v[194:197], v249 offset:1536
	ds_read_b128 v[198:201], v249 offset:1552
	v_mul_u32_u24_e32 v151, 0x1600, v246
	v_lshl_add_u32 v151, v248, 1, v151
	v_mov_b32_e32 v219, s64
	v_mov_b32_e32 v220, 0
	v_mov_b32_e32 v221, 0
	v_mov_b32_e32 v222, 0
	v_mov_b32_e32 v223, 0
	v_mov_b32_e32 v224, 0
	v_mov_b32_e32 v225, 0
	v_mov_b32_e32 v226, 0
	v_mov_b32_e32 v227, 0
	v_mov_b32_e32 v228, 0
	v_mov_b32_e32 v229, 0
	v_mov_b32_e32 v230, 0
	v_mov_b32_e32 v231, 0
	v_mov_b32_e32 v232, 0
	v_mov_b32_e32 v233, 0
	v_mov_b32_e32 v234, 0
	v_mov_b32_e32 v235, 0
	s_mul_i32 s56, s75, 0xb000
	s_lshl_b32 s57, s12, 10
	s_add_i32 s56, s56, s57
	v_mul_i32_i24_e32 v150, 0x5800, v216
	v_lshl_add_u32 v150, v215, 2, v150
	v_add_u32_e32 v150, s56, v150
	s_waitcnt lgkmcnt(8)
	v_fmamk_f32 v238, v238, 0x3a800000, v218
	v_fmamk_f32 v239, v239, 0x3a800000, v218
	v_fmamk_f32 v240, v240, 0x3a800000, v218
	v_fmamk_f32 v241, v241, 0x3a800000, v218
	v_fmamk_f32 v242, v242, 0x3a800000, v218
	v_fmamk_f32 v243, v243, 0x3a800000, v218
	v_fmamk_f32 v244, v244, 0x3a800000, v218
	v_fmamk_f32 v245, v245, 0x3a800000, v218
	v_rsq_f32_e32 v238, v238
	v_rsq_f32_e32 v239, v239
	v_rsq_f32_e32 v240, v240
	v_rsq_f32_e32 v241, v241
	v_rsq_f32_e32 v242, v242
	v_rsq_f32_e32 v243, v243
	v_rsq_f32_e32 v244, v244
	v_rsq_f32_e32 v245, v245
	ds_read_b128 v[202:205], v249 offset:2048
	ds_read_b128 v[206:209], v249 offset:2064
	ds_read_b128 v[210:213], v249 offset:2560
	ds_read_b128 v[128:131], v249 offset:2576
	ds_read_b128 v[132:135], v249 offset:3072
	ds_read_b128 v[136:139], v249 offset:3088
	ds_read_b128 v[140:143], v249 offset:3584
	ds_read_b128 v[144:147], v249 offset:3600
	v_pk_mul_f32 v[124:125], v[124:125], v[238:239] op_sel_hi:[1,0]
	v_pk_mul_f32 v[126:127], v[126:127], v[238:239] op_sel_hi:[1,0]
	v_pk_mul_f32 v[92:93], v[92:93], v[238:239] op_sel_hi:[1,0]
	v_pk_mul_f32 v[94:95], v[94:95], v[238:239] op_sel_hi:[1,0]
	v_pk_mul_f32 v[108:109], v[108:109], v[238:239] op_sel_hi:[1,0]
	v_pk_mul_f32 v[110:111], v[110:111], v[238:239] op_sel_hi:[1,0]
	v_pk_mul_f32 v[76:77], v[76:77], v[238:239] op_sel_hi:[1,0]
	v_pk_mul_f32 v[78:79], v[78:79], v[238:239] op_sel_hi:[1,0]
	v_pk_mul_f32 v[120:121], v[120:121], v[238:239] op_sel:[0,1] op_sel_hi:[1,1]
	v_pk_mul_f32 v[122:123], v[122:123], v[238:239] op_sel:[0,1] op_sel_hi:[1,1]
	v_pk_mul_f32 v[88:89], v[88:89], v[238:239] op_sel:[0,1] op_sel_hi:[1,1]
	v_pk_mul_f32 v[90:91], v[90:91], v[238:239] op_sel:[0,1] op_sel_hi:[1,1]
	v_pk_mul_f32 v[104:105], v[104:105], v[238:239] op_sel:[0,1] op_sel_hi:[1,1]
	v_pk_mul_f32 v[106:107], v[106:107], v[238:239] op_sel:[0,1] op_sel_hi:[1,1]
	v_pk_mul_f32 v[72:73], v[72:73], v[238:239] op_sel:[0,1] op_sel_hi:[1,1]
	v_pk_mul_f32 v[74:75], v[74:75], v[238:239] op_sel:[0,1] op_sel_hi:[1,1]
	v_pk_mul_f32 v[116:117], v[116:117], v[240:241] op_sel_hi:[1,0]
	v_pk_mul_f32 v[118:119], v[118:119], v[240:241] op_sel_hi:[1,0]
	v_pk_mul_f32 v[84:85], v[84:85], v[240:241] op_sel_hi:[1,0]
	v_pk_mul_f32 v[86:87], v[86:87], v[240:241] op_sel_hi:[1,0]
	v_pk_mul_f32 v[100:101], v[100:101], v[240:241] op_sel_hi:[1,0]
	v_pk_mul_f32 v[102:103], v[102:103], v[240:241] op_sel_hi:[1,0]
	v_pk_mul_f32 v[68:69], v[68:69], v[240:241] op_sel_hi:[1,0]
	v_pk_mul_f32 v[70:71], v[70:71], v[240:241] op_sel_hi:[1,0]
	v_pk_mul_f32 v[112:113], v[112:113], v[240:241] op_sel:[0,1] op_sel_hi:[1,1]
	v_pk_mul_f32 v[114:115], v[114:115], v[240:241] op_sel:[0,1] op_sel_hi:[1,1]
	v_pk_mul_f32 v[80:81], v[80:81], v[240:241] op_sel:[0,1] op_sel_hi:[1,1]
	v_pk_mul_f32 v[82:83], v[82:83], v[240:241] op_sel:[0,1] op_sel_hi:[1,1]
	v_pk_mul_f32 v[96:97], v[96:97], v[240:241] op_sel:[0,1] op_sel_hi:[1,1]
	v_pk_mul_f32 v[98:99], v[98:99], v[240:241] op_sel:[0,1] op_sel_hi:[1,1]
	v_pk_mul_f32 v[64:65], v[64:65], v[240:241] op_sel:[0,1] op_sel_hi:[1,1]
	v_pk_mul_f32 v[66:67], v[66:67], v[240:241] op_sel:[0,1] op_sel_hi:[1,1]
	v_pk_mul_f32 v[60:61], v[60:61], v[242:243] op_sel_hi:[1,0]
	v_pk_mul_f32 v[62:63], v[62:63], v[242:243] op_sel_hi:[1,0]
	v_pk_mul_f32 v[28:29], v[28:29], v[242:243] op_sel_hi:[1,0]
	v_pk_mul_f32 v[30:31], v[30:31], v[242:243] op_sel_hi:[1,0]
	v_pk_mul_f32 v[44:45], v[44:45], v[242:243] op_sel_hi:[1,0]
	v_pk_mul_f32 v[46:47], v[46:47], v[242:243] op_sel_hi:[1,0]
	v_pk_mul_f32 v[12:13], v[12:13], v[242:243] op_sel_hi:[1,0]
	v_pk_mul_f32 v[14:15], v[14:15], v[242:243] op_sel_hi:[1,0]
	v_pk_mul_f32 v[52:53], v[52:53], v[242:243] op_sel:[0,1] op_sel_hi:[1,1]
	v_pk_mul_f32 v[54:55], v[54:55], v[242:243] op_sel:[0,1] op_sel_hi:[1,1]
	v_pk_mul_f32 v[20:21], v[20:21], v[242:243] op_sel:[0,1] op_sel_hi:[1,1]
	v_pk_mul_f32 v[22:23], v[22:23], v[242:243] op_sel:[0,1] op_sel_hi:[1,1]
	v_pk_mul_f32 v[36:37], v[36:37], v[242:243] op_sel:[0,1] op_sel_hi:[1,1]
	v_pk_mul_f32 v[38:39], v[38:39], v[242:243] op_sel:[0,1] op_sel_hi:[1,1]
	v_pk_mul_f32 v[4:5], v[4:5], v[242:243] op_sel:[0,1] op_sel_hi:[1,1]
	v_pk_mul_f32 v[6:7], v[6:7], v[242:243] op_sel:[0,1] op_sel_hi:[1,1]
	v_pk_mul_f32 v[48:49], v[48:49], v[244:245] op_sel_hi:[1,0]
	v_pk_mul_f32 v[50:51], v[50:51], v[244:245] op_sel_hi:[1,0]
	v_pk_mul_f32 v[16:17], v[16:17], v[244:245] op_sel_hi:[1,0]
	v_pk_mul_f32 v[18:19], v[18:19], v[244:245] op_sel_hi:[1,0]
	v_pk_mul_f32 v[32:33], v[32:33], v[244:245] op_sel_hi:[1,0]
	v_pk_mul_f32 v[34:35], v[34:35], v[244:245] op_sel_hi:[1,0]
	v_pk_mul_f32 v[0:1], v[0:1], v[244:245] op_sel_hi:[1,0]
	v_pk_mul_f32 v[2:3], v[2:3], v[244:245] op_sel_hi:[1,0]
	v_pk_mul_f32 v[56:57], v[56:57], v[244:245] op_sel:[0,1] op_sel_hi:[1,1]
	v_pk_mul_f32 v[58:59], v[58:59], v[244:245] op_sel:[0,1] op_sel_hi:[1,1]
	v_pk_mul_f32 v[24:25], v[24:25], v[244:245] op_sel:[0,1] op_sel_hi:[1,1]
	v_pk_mul_f32 v[26:27], v[26:27], v[244:245] op_sel:[0,1] op_sel_hi:[1,1]
	v_pk_mul_f32 v[40:41], v[40:41], v[244:245] op_sel:[0,1] op_sel_hi:[1,1]
	v_pk_mul_f32 v[42:43], v[42:43], v[244:245] op_sel:[0,1] op_sel_hi:[1,1]
	v_pk_mul_f32 v[8:9], v[8:9], v[244:245] op_sel:[0,1] op_sel_hi:[1,1]
	v_pk_mul_f32 v[10:11], v[10:11], v[244:245] op_sel:[0,1] op_sel_hi:[1,1]
	s_waitcnt lgkmcnt(0)
; __device__ __forceinline__ f32x2 gelu_pk(f32x2 v) {
;     const f32x2 av = __builtin_elementwise_abs(v), d = av * 0.2316418882f + 1.0f;
;     __device__ __forceinline__ void operator()(const f32x4 (&acc)[2][2][4][2], const Unit& u, int wr, int wc, int fr, int fq) const {
;     ...
; #pragma unroll
;                     for (int m = 0; m < 4; ++m) {
;                         f32x4 cv;
;                         if (!samp) {
;                             const f32x4 prev = m ? v[m - 1] : hv;
; #pragma unroll
;                             for (int e = 0; e < 4; ++e) {
;                                 const int vi = __float_as_int(v[m][e]), pi = __float_as_int(prev[e]);
;                                 const int o1 = __builtin_amdgcn_mov_dpp(pi, 0x121, 0xf, 0xf, false);
;                                 const int o2 = __builtin_amdgcn_mov_dpp(pi, 0x122, 0xf, 0xf, false);
;                                 const float p1 = __int_as_float(__builtin_amdgcn_update_dpp(o1, vi, 0x111, 0xf, 0xf, false));
;                                 const float p2 = __int_as_float(__builtin_amdgcn_update_dpp(o2, vi, 0x112, 0xf, 0xf, false));
;                                 cv[e] = cb[e] + cw0[e] * p2 + cw1[e] * p1 + cw2[e] * v[m][e];
;                             }
;                         } else {
;                             const int ns = rowb + 16 * m + fr - MP;
;                             f32x4 s0 = (f32x4){0.f, 0.f, 0.f, 0.f}, s1 = s0;
;                             if (ns < NS) {
;                                 s0 = *(const f32x4*)(state + (size_t)(ns * 2 + 0) * FF2 + oc); s1 = *(const f32x4*)(state + (size_t)(ns * 2 + 1) * FF2 + oc);
;                                 *(f32x4*)(ncs + (size_t)(ns * 2 + 0) * FF2 + oc) = s1; *(f32x4*)(ncs + (size_t)(ns * 2 + 1) * FF2 + oc) = v[m];
;                             }
;                             cv = cb + cw0 * s0 + cw1 * s1 + cw2 * v[m];
;                         }
;                         if (bj == 0) cg[m] = gelu4(cv);
;                         else {
;                             const f32x4 r = cg[m] * cv;
;                             v2u w; w.x = cvt_pk_bf16(r[0], r[1]); w.y = cvt_pk_bf16(r[2], r[3]);
;                             *(v2u*)(ACT + (size_t)(rowb + 16 * m + fr) * FF + 128 * u.pn + 32 * wc + 8 * fq + 4 * n) = w;
;                         }
	v_mov_b32_dpp v220, v116 quad_perm:[0,1,2,3] row_mask:0xf bank_mask:0x8
	v_mov_b32_dpp v221, v117 quad_perm:[0,1,2,3] row_mask:0xf bank_mask:0x8
	v_mov_b32_dpp v222, v118 quad_perm:[0,1,2,3] row_mask:0xf bank_mask:0x8
	v_mov_b32_dpp v223, v119 quad_perm:[0,1,2,3] row_mask:0xf bank_mask:0x8
	v_pk_fma_f32 v[254:255], v[202:203], v[112:113], v[132:133]
	v_pk_fma_f32 v[148:149], v[204:205], v[114:115], v[134:135]
	v_fmac_f32_dpp v254, v112, v186 row_shr:1 row_mask:0xf bank_mask:0xf
	v_fmac_f32_dpp v255, v113, v187 row_shr:1 row_mask:0xf bank_mask:0xf
	v_fmac_f32_dpp v148, v114, v188 row_shr:1 row_mask:0xf bank_mask:0xf
	v_fmac_f32_dpp v149, v115, v189 row_shr:1 row_mask:0xf bank_mask:0xf
	v_fmac_f32_dpp v254, v112, v170 row_shr:2 row_mask:0xf bank_mask:0xf
	v_fmac_f32_dpp v255, v113, v171 row_shr:2 row_mask:0xf bank_mask:0xf
	v_fmac_f32_dpp v148, v114, v172 row_shr:2 row_mask:0xf bank_mask:0xf
	v_fmac_f32_dpp v149, v115, v173 row_shr:2 row_mask:0xf bank_mask:0xf
	v_fmac_f32_dpp v254, v220, v186 row_ror:1 row_mask:0xf bank_mask:0x1
	v_fmac_f32_dpp v255, v221, v187 row_ror:1 row_mask:0xf bank_mask:0x1
	v_fmac_f32_dpp v148, v222, v188 row_ror:1 row_mask:0xf bank_mask:0x1
	v_fmac_f32_dpp v149, v223, v189 row_ror:1 row_mask:0xf bank_mask:0x1
	v_fmac_f32_dpp v254, v220, v170 row_ror:2 row_mask:0xf bank_mask:0x1
	v_fmac_f32_dpp v255, v221, v171 row_ror:2 row_mask:0xf bank_mask:0x1
	v_fmac_f32_dpp v148, v222, v172 row_ror:2 row_mask:0xf bank_mask:0x1
	v_fmac_f32_dpp v149, v223, v173 row_ror:2 row_mask:0xf bank_mask:0x1
	v_fma_f32 v246, |v254|, s38, 1.0
	v_fma_f32 v247, |v255|, s38, 1.0
	v_fma_f32 v248, |v148|, s38, 1.0
	v_fma_f32 v249, |v149|, s38, 1.0
	v_mul_f32_e32 v250, v254, v254
	v_mul_f32_e32 v251, v255, v255
	v_mul_f32_e32 v252, v148, v148
	v_mul_f32_e32 v253, v149, v149
	v_rcp_f32_e32 v246, v246
	v_rcp_f32_e32 v247, v247
	v_rcp_f32_e32 v248, v248
	v_rcp_f32_e32 v249, v249
	v_mul_f32_e32 v250, s72, v250
	v_mul_f32_e32 v251, s72, v251
	v_mul_f32_e32 v252, s72, v252
	v_mul_f32_e32 v253, s72, v253
	v_exp_f32_e32 v250, v250
	v_exp_f32_e32 v251, v251
	v_exp_f32_e32 v252, v252
	v_exp_f32_e32 v253, v253
	v_fmamk_f32 v238, v246, 0x3f07dc22, v219
	v_fmamk_f32 v239, v247, 0x3f07dc22, v219
	v_fmamk_f32 v240, v248, 0x3f07dc22, v219
	v_fmamk_f32 v241, v249, 0x3f07dc22, v219
	v_fma_f32 v238, v246, v238, s66
	v_fma_f32 v239, v247, v239, s66
	v_fma_f32 v240, v248, v240, s66
	v_fma_f32 v241, v249, v241, s66
	v_fma_f32 v238, v246, v238, s68
	v_fma_f32 v239, v247, v239, s68
	v_fma_f32 v240, v248, v240, s68
	v_fma_f32 v241, v249, v241, s68
	v_fma_f32 v238, v246, v238, s70
	v_fma_f32 v239, v247, v239, s70
	v_fma_f32 v240, v248, v240, s70
	v_fma_f32 v241, v249, v241, s70
	v_mul_f32_e32 v238, v246, v238
	v_mul_f32_e32 v239, v247, v239
	v_mul_f32_e32 v240, v248, v240
	v_mul_f32_e32 v241, v249, v241
	v_mul_f32_e32 v238, v250, v238
	v_mul_f32_e32 v239, v251, v239
	v_mul_f32_e32 v240, v252, v240
	v_mul_f32_e32 v241, v253, v241
	v_max_f32_e32 v246, 0, v254
	v_max_f32_e32 v247, 0, v255
	v_max_f32_e32 v248, 0, v148
	v_max_f32_e32 v249, 0, v149
	v_fma_f32 v238, -|v254|, v238, v246
	v_fma_f32 v239, -|v255|, v239, v247
	v_fma_f32 v240, -|v148|, v240, v248
	v_fma_f32 v241, -|v149|, v241, v249
	v_mov_b32_dpp v220, v100 quad_perm:[0,1,2,3] row_mask:0xf bank_mask:0x8
	v_mov_b32_dpp v221, v101 quad_perm:[0,1,2,3] row_mask:0xf bank_mask:0x8
	v_mov_b32_dpp v222, v102 quad_perm:[0,1,2,3] row_mask:0xf bank_mask:0x8
	v_mov_b32_dpp v223, v103 quad_perm:[0,1,2,3] row_mask:0xf bank_mask:0x8
	v_pk_fma_f32 v[254:255], v[210:211], v[96:97], v[140:141]
	v_pk_fma_f32 v[148:149], v[212:213], v[98:99], v[142:143]
	v_fmac_f32_dpp v254, v96, v194 row_shr:1 row_mask:0xf bank_mask:0xf
	v_fmac_f32_dpp v255, v97, v195 row_shr:1 row_mask:0xf bank_mask:0xf
	v_fmac_f32_dpp v148, v98, v196 row_shr:1 row_mask:0xf bank_mask:0xf
	v_fmac_f32_dpp v149, v99, v197 row_shr:1 row_mask:0xf bank_mask:0xf
	v_fmac_f32_dpp v254, v96, v178 row_shr:2 row_mask:0xf bank_mask:0xf
	v_fmac_f32_dpp v255, v97, v179 row_shr:2 row_mask:0xf bank_mask:0xf
	v_fmac_f32_dpp v148, v98, v180 row_shr:2 row_mask:0xf bank_mask:0xf
	v_fmac_f32_dpp v149, v99, v181 row_shr:2 row_mask:0xf bank_mask:0xf
	v_fmac_f32_dpp v254, v220, v194 row_ror:1 row_mask:0xf bank_mask:0x1
	v_fmac_f32_dpp v255, v221, v195 row_ror:1 row_mask:0xf bank_mask:0x1
	v_fmac_f32_dpp v148, v222, v196 row_ror:1 row_mask:0xf bank_mask:0x1
	v_fmac_f32_dpp v149, v223, v197 row_ror:1 row_mask:0xf bank_mask:0x1
	v_fmac_f32_dpp v254, v220, v178 row_ror:2 row_mask:0xf bank_mask:0x1
	v_fmac_f32_dpp v255, v221, v179 row_ror:2 row_mask:0xf bank_mask:0x1
	v_fmac_f32_dpp v148, v222, v180 row_ror:2 row_mask:0xf bank_mask:0x1
	v_fmac_f32_dpp v149, v223, v181 row_ror:2 row_mask:0xf bank_mask:0x1
	v_pk_mul_f32 v[254:255], v[238:239], v[254:255]
	v_pk_mul_f32 v[148:149], v[240:241], v[148:149]
	v_cvt_pk_bf16_f32 v242, v254, v255
	v_cvt_pk_bf16_f32 v243, v148, v149
	v_mov_b32_dpp v220, v84 quad_perm:[0,1,2,3] row_mask:0xf bank_mask:0x8
	v_mov_b32_dpp v221, v85 quad_perm:[0,1,2,3] row_mask:0xf bank_mask:0x8
	v_mov_b32_dpp v222, v86 quad_perm:[0,1,2,3] row_mask:0xf bank_mask:0x8
	v_mov_b32_dpp v223, v87 quad_perm:[0,1,2,3] row_mask:0xf bank_mask:0x8
	v_pk_fma_f32 v[254:255], v[206:207], v[80:81], v[136:137]
	v_pk_fma_f32 v[148:149], v[208:209], v[82:83], v[138:139]
	v_fmac_f32_dpp v254, v80, v190 row_shr:1 row_mask:0xf bank_mask:0xf
	v_fmac_f32_dpp v255, v81, v191 row_shr:1 row_mask:0xf bank_mask:0xf
	v_fmac_f32_dpp v148, v82, v192 row_shr:1 row_mask:0xf bank_mask:0xf
	v_fmac_f32_dpp v149, v83, v193 row_shr:1 row_mask:0xf bank_mask:0xf
	v_fmac_f32_dpp v254, v80, v174 row_shr:2 row_mask:0xf bank_mask:0xf
; __device__ __forceinline__ f32x2 gelu_pk(f32x2 v) {
;     const f32x2 av = __builtin_elementwise_abs(v), d = av * 0.2316418882f + 1.0f;
;     __device__ __forceinline__ void operator()(const f32x4 (&acc)[2][2][4][2], const Unit& u, int wr, int wc, int fr, int fq) const {
;     ...
; #pragma unroll
;                     for (int m = 0; m < 4; ++m) {
;                         f32x4 cv;
;                         if (!samp) {
;                             const f32x4 prev = m ? v[m - 1] : hv;
; #pragma unroll
;                             for (int e = 0; e < 4; ++e) {
;                                 const int vi = __float_as_int(v[m][e]), pi = __float_as_int(prev[e]);
;                                 const int o1 = __builtin_amdgcn_mov_dpp(pi, 0x121, 0xf, 0xf, false);
;                                 const int o2 = __builtin_amdgcn_mov_dpp(pi, 0x122, 0xf, 0xf, false);
;                                 const float p1 = __int_as_float(__builtin_amdgcn_update_dpp(o1, vi, 0x111, 0xf, 0xf, false));
;                                 const float p2 = __int_as_float(__builtin_amdgcn_update_dpp(o2, vi, 0x112, 0xf, 0xf, false));
;                                 cv[e] = cb[e] + cw0[e] * p2 + cw1[e] * p1 + cw2[e] * v[m][e];
;                             }
;                         } else {
;                             const int ns = rowb + 16 * m + fr - MP;
;                             f32x4 s0 = (f32x4){0.f, 0.f, 0.f, 0.f}, s1 = s0;
;                             if (ns < NS) {
;                                 s0 = *(const f32x4*)(state + (size_t)(ns * 2 + 0) * FF2 + oc); s1 = *(const f32x4*)(state + (size_t)(ns * 2 + 1) * FF2 + oc);
;                                 *(f32x4*)(ncs + (size_t)(ns * 2 + 0) * FF2 + oc) = s1; *(f32x4*)(ncs + (size_t)(ns * 2 + 1) * FF2 + oc) = v[m];
;                             }
;                             cv = cb + cw0 * s0 + cw1 * s1 + cw2 * v[m];
;                         }
;                         if (bj == 0) cg[m] = gelu4(cv);
;                         else {
;                             const f32x4 r = cg[m] * cv;
;                             v2u w; w.x = cvt_pk_bf16(r[0], r[1]); w.y = cvt_pk_bf16(r[2], r[3]);
;                             *(v2u*)(ACT + (size_t)(rowb + 16 * m + fr) * FF + 128 * u.pn + 32 * wc + 8 * fq + 4 * n) = w;
;                         }
	v_fmac_f32_dpp v255, v81, v175 row_shr:2 row_mask:0xf bank_mask:0xf
	v_fmac_f32_dpp v148, v82, v176 row_shr:2 row_mask:0xf bank_mask:0xf
	v_fmac_f32_dpp v149, v83, v177 row_shr:2 row_mask:0xf bank_mask:0xf
	v_fmac_f32_dpp v254, v220, v190 row_ror:1 row_mask:0xf bank_mask:0x1
	v_fmac_f32_dpp v255, v221, v191 row_ror:1 row_mask:0xf bank_mask:0x1
	v_fmac_f32_dpp v148, v222, v192 row_ror:1 row_mask:0xf bank_mask:0x1
	v_fmac_f32_dpp v149, v223, v193 row_ror:1 row_mask:0xf bank_mask:0x1
	v_fmac_f32_dpp v254, v220, v174 row_ror:2 row_mask:0xf bank_mask:0x1
	v_fmac_f32_dpp v255, v221, v175 row_ror:2 row_mask:0xf bank_mask:0x1
	v_fmac_f32_dpp v148, v222, v176 row_ror:2 row_mask:0xf bank_mask:0x1
	v_fmac_f32_dpp v149, v223, v177 row_ror:2 row_mask:0xf bank_mask:0x1
	v_fma_f32 v246, |v254|, s38, 1.0
	v_fma_f32 v247, |v255|, s38, 1.0
	v_fma_f32 v248, |v148|, s38, 1.0
	v_fma_f32 v249, |v149|, s38, 1.0
	v_mul_f32_e32 v250, v254, v254
	v_mul_f32_e32 v251, v255, v255
	v_mul_f32_e32 v252, v148, v148
	v_mul_f32_e32 v253, v149, v149
	v_rcp_f32_e32 v246, v246
	v_rcp_f32_e32 v247, v247
	v_rcp_f32_e32 v248, v248
	v_rcp_f32_e32 v249, v249
	v_mul_f32_e32 v250, s72, v250
	v_mul_f32_e32 v251, s72, v251
	v_mul_f32_e32 v252, s72, v252
	v_mul_f32_e32 v253, s72, v253
	v_exp_f32_e32 v250, v250
	v_exp_f32_e32 v251, v251
	v_exp_f32_e32 v252, v252
	v_exp_f32_e32 v253, v253
	v_fmamk_f32 v238, v246, 0x3f07dc22, v219
	v_fmamk_f32 v239, v247, 0x3f07dc22, v219
	v_fmamk_f32 v240, v248, 0x3f07dc22, v219
	v_fmamk_f32 v241, v249, 0x3f07dc22, v219
	v_fma_f32 v238, v246, v238, s66
	v_fma_f32 v239, v247, v239, s66
	v_fma_f32 v240, v248, v240, s66
	v_fma_f32 v241, v249, v241, s66
	v_fma_f32 v238, v246, v238, s68
	v_fma_f32 v239, v247, v239, s68
	v_fma_f32 v240, v248, v240, s68
	v_fma_f32 v241, v249, v241, s68
	v_fma_f32 v238, v246, v238, s70
	v_fma_f32 v239, v247, v239, s70
	v_fma_f32 v240, v248, v240, s70
	v_fma_f32 v241, v249, v241, s70
	v_mul_f32_e32 v238, v246, v238
	v_mul_f32_e32 v239, v247, v239
	v_mul_f32_e32 v240, v248, v240
	v_mul_f32_e32 v241, v249, v241
	v_mul_f32_e32 v238, v250, v238
	v_mul_f32_e32 v239, v251, v239
	v_mul_f32_e32 v240, v252, v240
	v_mul_f32_e32 v241, v253, v241
	v_max_f32_e32 v246, 0, v254
	v_max_f32_e32 v247, 0, v255
	v_max_f32_e32 v248, 0, v148
	v_max_f32_e32 v249, 0, v149
	v_fma_f32 v238, -|v254|, v238, v246
	v_fma_f32 v239, -|v255|, v239, v247
	v_fma_f32 v240, -|v148|, v240, v248
	v_fma_f32 v241, -|v149|, v241, v249
	v_mov_b32_dpp v220, v68 quad_perm:[0,1,2,3] row_mask:0xf bank_mask:0x8
	v_mov_b32_dpp v221, v69 quad_perm:[0,1,2,3] row_mask:0xf bank_mask:0x8
	v_mov_b32_dpp v222, v70 quad_perm:[0,1,2,3] row_mask:0xf bank_mask:0x8
	v_mov_b32_dpp v223, v71 quad_perm:[0,1,2,3] row_mask:0xf bank_mask:0x8
	v_pk_fma_f32 v[254:255], v[128:129], v[64:65], v[144:145]
	v_pk_fma_f32 v[148:149], v[130:131], v[66:67], v[146:147]
	v_fmac_f32_dpp v254, v64, v198 row_shr:1 row_mask:0xf bank_mask:0xf
	v_fmac_f32_dpp v255, v65, v199 row_shr:1 row_mask:0xf bank_mask:0xf
	v_fmac_f32_dpp v148, v66, v200 row_shr:1 row_mask:0xf bank_mask:0xf
	v_fmac_f32_dpp v149, v67, v201 row_shr:1 row_mask:0xf bank_mask:0xf
	v_fmac_f32_dpp v254, v64, v182 row_shr:2 row_mask:0xf bank_mask:0xf
	v_fmac_f32_dpp v255, v65, v183 row_shr:2 row_mask:0xf bank_mask:0xf
	v_fmac_f32_dpp v148, v66, v184 row_shr:2 row_mask:0xf bank_mask:0xf
	v_fmac_f32_dpp v149, v67, v185 row_shr:2 row_mask:0xf bank_mask:0xf
	v_fmac_f32_dpp v254, v220, v198 row_ror:1 row_mask:0xf bank_mask:0x1
	v_fmac_f32_dpp v255, v221, v199 row_ror:1 row_mask:0xf bank_mask:0x1
	v_fmac_f32_dpp v148, v222, v200 row_ror:1 row_mask:0xf bank_mask:0x1
	v_fmac_f32_dpp v149, v223, v201 row_ror:1 row_mask:0xf bank_mask:0x1
	v_fmac_f32_dpp v254, v220, v182 row_ror:2 row_mask:0xf bank_mask:0x1
	v_fmac_f32_dpp v255, v221, v183 row_ror:2 row_mask:0xf bank_mask:0x1
	v_fmac_f32_dpp v148, v222, v184 row_ror:2 row_mask:0xf bank_mask:0x1
	v_fmac_f32_dpp v149, v223, v185 row_ror:2 row_mask:0xf bank_mask:0x1
	v_pk_mul_f32 v[254:255], v[238:239], v[254:255]
	v_pk_mul_f32 v[148:149], v[240:241], v[148:149]
	v_cvt_pk_bf16_f32 v244, v254, v255
	v_cvt_pk_bf16_f32 v245, v148, v149
	s_add_u32 s56, s46, 0x42000
	s_addc_u32 s57, s47, 0
	global_store_dwordx4 v151, v[242:245], s[56:57]
	v_mov_b32_e32 v112, 0
	v_mov_b32_e32 v113, 0
	v_mov_b32_e32 v114, 0
	v_mov_b32_e32 v115, 0
	v_mov_b32_dpp v112, v120 quad_perm:[0,1,2,3] row_mask:0xf bank_mask:0x8
	v_mov_b32_dpp v113, v121 quad_perm:[0,1,2,3] row_mask:0xf bank_mask:0x8
	v_mov_b32_dpp v114, v122 quad_perm:[0,1,2,3] row_mask:0xf bank_mask:0x8
	v_mov_b32_dpp v115, v123 quad_perm:[0,1,2,3] row_mask:0xf bank_mask:0x8
	v_pk_fma_f32 v[254:255], v[202:203], v[116:117], v[132:133]
	v_pk_fma_f32 v[148:149], v[204:205], v[118:119], v[134:135]
	v_fmac_f32_dpp v254, v116, v186 row_shr:1 row_mask:0xf bank_mask:0xf
	v_fmac_f32_dpp v255, v117, v187 row_shr:1 row_mask:0xf bank_mask:0xf
	v_fmac_f32_dpp v148, v118, v188 row_shr:1 row_mask:0xf bank_mask:0xf
	v_fmac_f32_dpp v149, v119, v189 row_shr:1 row_mask:0xf bank_mask:0xf
	v_fmac_f32_dpp v254, v116, v170 row_shr:2 row_mask:0xf bank_mask:0xf
	v_fmac_f32_dpp v255, v117, v171 row_shr:2 row_mask:0xf bank_mask:0xf
	v_fmac_f32_dpp v148, v118, v172 row_shr:2 row_mask:0xf bank_mask:0xf
	v_fmac_f32_dpp v149, v119, v173 row_shr:2 row_mask:0xf bank_mask:0xf
	v_fmac_f32_dpp v254, v112, v186 row_ror:1 row_mask:0xf bank_mask:0x1
	v_fmac_f32_dpp v255, v113, v187 row_ror:1 row_mask:0xf bank_mask:0x1
	v_fmac_f32_dpp v148, v114, v188 row_ror:1 row_mask:0xf bank_mask:0x1
	v_fmac_f32_dpp v149, v115, v189 row_ror:1 row_mask:0xf bank_mask:0x1
	v_fmac_f32_dpp v254, v112, v170 row_ror:2 row_mask:0xf bank_mask:0x1
; __device__ __forceinline__ f32x2 gelu_pk(f32x2 v) {
;     const f32x2 av = __builtin_elementwise_abs(v), d = av * 0.2316418882f + 1.0f;
;     __device__ __forceinline__ void operator()(const f32x4 (&acc)[2][2][4][2], const Unit& u, int wr, int wc, int fr, int fq) const {
;     ...
; #pragma unroll
;                     for (int m = 0; m < 4; ++m) {
;                         f32x4 cv;
;                         if (!samp) {
;                             const f32x4 prev = m ? v[m - 1] : hv;
; #pragma unroll
;                             for (int e = 0; e < 4; ++e) {
;                                 const int vi = __float_as_int(v[m][e]), pi = __float_as_int(prev[e]);
;                                 const int o1 = __builtin_amdgcn_mov_dpp(pi, 0x121, 0xf, 0xf, false);
;                                 const int o2 = __builtin_amdgcn_mov_dpp(pi, 0x122, 0xf, 0xf, false);
;                                 const float p1 = __int_as_float(__builtin_amdgcn_update_dpp(o1, vi, 0x111, 0xf, 0xf, false));
;                                 const float p2 = __int_as_float(__builtin_amdgcn_update_dpp(o2, vi, 0x112, 0xf, 0xf, false));
;                                 cv[e] = cb[e] + cw0[e] * p2 + cw1[e] * p1 + cw2[e] * v[m][e];
;                             }
;                         } else {
;                             const int ns = rowb + 16 * m + fr - MP;
;                             f32x4 s0 = (f32x4){0.f, 0.f, 0.f, 0.f}, s1 = s0;
;                             if (ns < NS) {
;                                 s0 = *(const f32x4*)(state + (size_t)(ns * 2 + 0) * FF2 + oc); s1 = *(const f32x4*)(state + (size_t)(ns * 2 + 1) * FF2 + oc);
;                                 *(f32x4*)(ncs + (size_t)(ns * 2 + 0) * FF2 + oc) = s1; *(f32x4*)(ncs + (size_t)(ns * 2 + 1) * FF2 + oc) = v[m];
;                             }
;                             cv = cb + cw0 * s0 + cw1 * s1 + cw2 * v[m];
;                         }
;                         if (bj == 0) cg[m] = gelu4(cv);
;                         else {
;                             const f32x4 r = cg[m] * cv;
;                             v2u w; w.x = cvt_pk_bf16(r[0], r[1]); w.y = cvt_pk_bf16(r[2], r[3]);
;                             *(v2u*)(ACT + (size_t)(rowb + 16 * m + fr) * FF + 128 * u.pn + 32 * wc + 8 * fq + 4 * n) = w;
;                         }
	v_fmac_f32_dpp v255, v113, v171 row_ror:2 row_mask:0xf bank_mask:0x1
	v_fmac_f32_dpp v148, v114, v172 row_ror:2 row_mask:0xf bank_mask:0x1
	v_fmac_f32_dpp v149, v115, v173 row_ror:2 row_mask:0xf bank_mask:0x1
	v_fma_f32 v246, |v254|, s38, 1.0
	v_fma_f32 v247, |v255|, s38, 1.0
	v_fma_f32 v248, |v148|, s38, 1.0
	v_fma_f32 v249, |v149|, s38, 1.0
	v_mul_f32_e32 v250, v254, v254
	v_mul_f32_e32 v251, v255, v255
	v_mul_f32_e32 v252, v148, v148
	v_mul_f32_e32 v253, v149, v149
	v_rcp_f32_e32 v246, v246
	v_rcp_f32_e32 v247, v247
	v_rcp_f32_e32 v248, v248
	v_rcp_f32_e32 v249, v249
	v_mul_f32_e32 v250, s72, v250
	v_mul_f32_e32 v251, s72, v251
	v_mul_f32_e32 v252, s72, v252
	v_mul_f32_e32 v253, s72, v253
	v_exp_f32_e32 v250, v250
	v_exp_f32_e32 v251, v251
	v_exp_f32_e32 v252, v252
	v_exp_f32_e32 v253, v253
	v_fmamk_f32 v238, v246, 0x3f07dc22, v219
	v_fmamk_f32 v239, v247, 0x3f07dc22, v219
	v_fmamk_f32 v240, v248, 0x3f07dc22, v219
	v_fmamk_f32 v241, v249, 0x3f07dc22, v219
	v_fma_f32 v238, v246, v238, s66
	v_fma_f32 v239, v247, v239, s66
	v_fma_f32 v240, v248, v240, s66
	v_fma_f32 v241, v249, v241, s66
	v_fma_f32 v238, v246, v238, s68
	v_fma_f32 v239, v247, v239, s68
	v_fma_f32 v240, v248, v240, s68
	v_fma_f32 v241, v249, v241, s68
	v_fma_f32 v238, v246, v238, s70
	v_fma_f32 v239, v247, v239, s70
	v_fma_f32 v240, v248, v240, s70
	v_fma_f32 v241, v249, v241, s70
	v_mul_f32_e32 v238, v246, v238
	v_mul_f32_e32 v239, v247, v239
	v_mul_f32_e32 v240, v248, v240
	v_mul_f32_e32 v241, v249, v241
	v_mul_f32_e32 v238, v250, v238
	v_mul_f32_e32 v239, v251, v239
	v_mul_f32_e32 v240, v252, v240
	v_mul_f32_e32 v241, v253, v241
	v_max_f32_e32 v246, 0, v254
	v_max_f32_e32 v247, 0, v255
	v_max_f32_e32 v248, 0, v148
	v_max_f32_e32 v249, 0, v149
	v_fma_f32 v238, -|v254|, v238, v246
	v_fma_f32 v239, -|v255|, v239, v247
	v_fma_f32 v240, -|v148|, v240, v248
	v_fma_f32 v241, -|v149|, v241, v249
	v_mov_b32_dpp v112, v104 quad_perm:[0,1,2,3] row_mask:0xf bank_mask:0x8
	v_mov_b32_dpp v113, v105 quad_perm:[0,1,2,3] row_mask:0xf bank_mask:0x8
	v_mov_b32_dpp v114, v106 quad_perm:[0,1,2,3] row_mask:0xf bank_mask:0x8
	v_mov_b32_dpp v115, v107 quad_perm:[0,1,2,3] row_mask:0xf bank_mask:0x8
	v_pk_fma_f32 v[254:255], v[210:211], v[100:101], v[140:141]
	v_pk_fma_f32 v[148:149], v[212:213], v[102:103], v[142:143]
	v_fmac_f32_dpp v254, v100, v194 row_shr:1 row_mask:0xf bank_mask:0xf
	v_fmac_f32_dpp v255, v101, v195 row_shr:1 row_mask:0xf bank_mask:0xf
	v_fmac_f32_dpp v148, v102, v196 row_shr:1 row_mask:0xf bank_mask:0xf
	v_fmac_f32_dpp v149, v103, v197 row_shr:1 row_mask:0xf bank_mask:0xf
	v_fmac_f32_dpp v254, v100, v178 row_shr:2 row_mask:0xf bank_mask:0xf
	v_fmac_f32_dpp v255, v101, v179 row_shr:2 row_mask:0xf bank_mask:0xf
	v_fmac_f32_dpp v148, v102, v180 row_shr:2 row_mask:0xf bank_mask:0xf
	v_fmac_f32_dpp v149, v103, v181 row_shr:2 row_mask:0xf bank_mask:0xf
	v_fmac_f32_dpp v254, v112, v194 row_ror:1 row_mask:0xf bank_mask:0x1
	v_fmac_f32_dpp v255, v113, v195 row_ror:1 row_mask:0xf bank_mask:0x1
	v_fmac_f32_dpp v148, v114, v196 row_ror:1 row_mask:0xf bank_mask:0x1
	v_fmac_f32_dpp v149, v115, v197 row_ror:1 row_mask:0xf bank_mask:0x1
	v_fmac_f32_dpp v254, v112, v178 row_ror:2 row_mask:0xf bank_mask:0x1
	v_fmac_f32_dpp v255, v113, v179 row_ror:2 row_mask:0xf bank_mask:0x1
	v_fmac_f32_dpp v148, v114, v180 row_ror:2 row_mask:0xf bank_mask:0x1
	v_fmac_f32_dpp v149, v115, v181 row_ror:2 row_mask:0xf bank_mask:0x1
	v_pk_mul_f32 v[254:255], v[238:239], v[254:255]
	v_pk_mul_f32 v[148:149], v[240:241], v[148:149]
	v_cvt_pk_bf16_f32 v242, v254, v255
	v_cvt_pk_bf16_f32 v243, v148, v149
	v_mov_b32_dpp v112, v88 quad_perm:[0,1,2,3] row_mask:0xf bank_mask:0x8
	v_mov_b32_dpp v113, v89 quad_perm:[0,1,2,3] row_mask:0xf bank_mask:0x8
	v_mov_b32_dpp v114, v90 quad_perm:[0,1,2,3] row_mask:0xf bank_mask:0x8
	v_mov_b32_dpp v115, v91 quad_perm:[0,1,2,3] row_mask:0xf bank_mask:0x8
	v_pk_fma_f32 v[254:255], v[206:207], v[84:85], v[136:137]
	v_pk_fma_f32 v[148:149], v[208:209], v[86:87], v[138:139]
	v_fmac_f32_dpp v254, v84, v190 row_shr:1 row_mask:0xf bank_mask:0xf
	v_fmac_f32_dpp v255, v85, v191 row_shr:1 row_mask:0xf bank_mask:0xf
	v_fmac_f32_dpp v148, v86, v192 row_shr:1 row_mask:0xf bank_mask:0xf
	v_fmac_f32_dpp v149, v87, v193 row_shr:1 row_mask:0xf bank_mask:0xf
	v_fmac_f32_dpp v254, v84, v174 row_shr:2 row_mask:0xf bank_mask:0xf
	v_fmac_f32_dpp v255, v85, v175 row_shr:2 row_mask:0xf bank_mask:0xf
	v_fmac_f32_dpp v148, v86, v176 row_shr:2 row_mask:0xf bank_mask:0xf
	v_fmac_f32_dpp v149, v87, v177 row_shr:2 row_mask:0xf bank_mask:0xf
;     __device__ __forceinline__ void operator()(const f32x4 (&acc)[2][2][4][2], const Unit& u, int wr, int wc, int fr, int fq) const {
;     ...
;                         if ((blk & 31) != 0 && fr >= 14) hv = *(const f32x4*)(HALO + (size_t)(2 * blk + fr - 14) * FF2 + cgc);
;                         if ((u.pm & 7) == 7 && ai == 1 && wr == 1 && fr >= 14) *(f32x4*)(ncp + (size_t)((u.pm >> 3) * 2 + (fr - 14)) * FF2 + oc) = v[3];
;                     }
; #pragma unroll
;                     for (int m = 0; m < 4; ++m) {
;                         f32x4 cv;
;                         if (!samp) {
;                             const f32x4 prev = m ? v[m - 1] : hv;
; #pragma unroll
;                             for (int e = 0; e < 4; ++e) {
;                                 const int vi = __float_as_int(v[m][e]), pi = __float_as_int(prev[e]);
;                                 const int o1 = __builtin_amdgcn_mov_dpp(pi, 0x121, 0xf, 0xf, false);
;                                 const int o2 = __builtin_amdgcn_mov_dpp(pi, 0x122, 0xf, 0xf, false);
;                                 const float p1 = __int_as_float(__builtin_amdgcn_update_dpp(o1, vi, 0x111, 0xf, 0xf, false));
;                                 const float p2 = __int_as_float(__builtin_amdgcn_update_dpp(o2, vi, 0x112, 0xf, 0xf, false));
;                                 cv[e] = cb[e] + cw0[e] * p2 + cw1[e] * p1 + cw2[e] * v[m][e];
;                             }
;                         } else {
;                             const int ns = rowb + 16 * m + fr - MP;
;                             f32x4 s0 = (f32x4){0.f, 0.f, 0.f, 0.f}, s1 = s0;
;                             if (ns < NS) {
;                                 s0 = *(const f32x4*)(state + (size_t)(ns * 2 + 0) * FF2 + oc); s1 = *(const f32x4*)(state + (size_t)(ns * 2 + 1) * FF2 + oc);
;                                 *(f32x4*)(ncs + (size_t)(ns * 2 + 0) * FF2 + oc) = s1; *(f32x4*)(ncs + (size_t)(ns * 2 + 1) * FF2 + oc) = v[m];
;                             }
;                             cv = cb + cw0 * s0 + cw1 * s1 + cw2 * v[m];
;                         }
;                         if (bj == 0) cg[m] = gelu4(cv);
;                         else {
;                             const f32x4 r = cg[m] * cv;
;                             v2u w; w.x = cvt_pk_bf16(r[0], r[1]); w.y = cvt_pk_bf16(r[2], r[3]);
	v_fmac_f32_dpp v254, v112, v190 row_ror:1 row_mask:0xf bank_mask:0x1
	v_fmac_f32_dpp v255, v113, v191 row_ror:1 row_mask:0xf bank_mask:0x1
	v_fmac_f32_dpp v148, v114, v192 row_ror:1 row_mask:0xf bank_mask:0x1
	v_fmac_f32_dpp v149, v115, v193 row_ror:1 row_mask:0xf bank_mask:0x1
	v_fmac_f32_dpp v254, v112, v174 row_ror:2 row_mask:0xf bank_mask:0x1
	v_fmac_f32_dpp v255, v113, v175 row_ror:2 row_mask:0xf bank_mask:0x1
	v_fmac_f32_dpp v148, v114, v176 row_ror:2 row_mask:0xf bank_mask:0x1
	v_fmac_f32_dpp v149, v115, v177 row_ror:2 row_mask:0xf bank_mask:0x1
	v_fma_f32 v246, |v254|, s38, 1.0
	v_fma_f32 v247, |v255|, s38, 1.0
	v_fma_f32 v248, |v148|, s38, 1.0
	v_fma_f32 v249, |v149|, s38, 1.0
	v_mul_f32_e32 v250, v254, v254
	v_mul_f32_e32 v251, v255, v255
	v_mul_f32_e32 v252, v148, v148
	v_mul_f32_e32 v253, v149, v149
	v_rcp_f32_e32 v246, v246
	v_rcp_f32_e32 v247, v247
	v_rcp_f32_e32 v248, v248
	v_rcp_f32_e32 v249, v249
	v_mul_f32_e32 v250, s72, v250
	v_mul_f32_e32 v251, s72, v251
	v_mul_f32_e32 v252, s72, v252
	v_mul_f32_e32 v253, s72, v253
	v_exp_f32_e32 v250, v250
	v_exp_f32_e32 v251, v251
	v_exp_f32_e32 v252, v252
	v_exp_f32_e32 v253, v253
	v_fmamk_f32 v238, v246, 0x3f07dc22, v219
	v_fmamk_f32 v239, v247, 0x3f07dc22, v219
	v_fmamk_f32 v240, v248, 0x3f07dc22, v219
	v_fmamk_f32 v241, v249, 0x3f07dc22, v219
	v_fma_f32 v238, v246, v238, s66
	v_fma_f32 v239, v247, v239, s66
	v_fma_f32 v240, v248, v240, s66
	v_fma_f32 v241, v249, v241, s66
	v_fma_f32 v238, v246, v238, s68
	v_fma_f32 v239, v247, v239, s68
	v_fma_f32 v240, v248, v240, s68
	v_fma_f32 v241, v249, v241, s68
	v_fma_f32 v238, v246, v238, s70
	v_fma_f32 v239, v247, v239, s70
	v_fma_f32 v240, v248, v240, s70
	v_fma_f32 v241, v249, v241, s70
	v_mul_f32_e32 v238, v246, v238
	v_mul_f32_e32 v239, v247, v239
	v_mul_f32_e32 v240, v248, v240
	v_mul_f32_e32 v241, v249, v241
	v_mul_f32_e32 v238, v250, v238
	v_mul_f32_e32 v239, v251, v239
	v_mul_f32_e32 v240, v252, v240
	v_mul_f32_e32 v241, v253, v241
	v_max_f32_e32 v246, 0, v254
	v_max_f32_e32 v247, 0, v255
	v_max_f32_e32 v248, 0, v148
	v_max_f32_e32 v249, 0, v149
	v_fma_f32 v238, -|v254|, v238, v246
	v_fma_f32 v239, -|v255|, v239, v247
	v_fma_f32 v240, -|v148|, v240, v248
	v_fma_f32 v241, -|v149|, v241, v249
	v_mov_b32_dpp v112, v72 quad_perm:[0,1,2,3] row_mask:0xf bank_mask:0x8
	v_mov_b32_dpp v113, v73 quad_perm:[0,1,2,3] row_mask:0xf bank_mask:0x8
	v_mov_b32_dpp v114, v74 quad_perm:[0,1,2,3] row_mask:0xf bank_mask:0x8
	v_mov_b32_dpp v115, v75 quad_perm:[0,1,2,3] row_mask:0xf bank_mask:0x8
	v_pk_fma_f32 v[254:255], v[128:129], v[68:69], v[144:145]
	v_pk_fma_f32 v[148:149], v[130:131], v[70:71], v[146:147]
	v_fmac_f32_dpp v254, v68, v198 row_shr:1 row_mask:0xf bank_mask:0xf
	v_fmac_f32_dpp v255, v69, v199 row_shr:1 row_mask:0xf bank_mask:0xf
	v_fmac_f32_dpp v148, v70, v200 row_shr:1 row_mask:0xf bank_mask:0xf
	v_fmac_f32_dpp v149, v71, v201 row_shr:1 row_mask:0xf bank_mask:0xf
	v_fmac_f32_dpp v254, v68, v182 row_shr:2 row_mask:0xf bank_mask:0xf
	v_fmac_f32_dpp v255, v69, v183 row_shr:2 row_mask:0xf bank_mask:0xf
	v_fmac_f32_dpp v148, v70, v184 row_shr:2 row_mask:0xf bank_mask:0xf
	v_fmac_f32_dpp v149, v71, v185 row_shr:2 row_mask:0xf bank_mask:0xf
	v_fmac_f32_dpp v254, v112, v198 row_ror:1 row_mask:0xf bank_mask:0x1
	v_fmac_f32_dpp v255, v113, v199 row_ror:1 row_mask:0xf bank_mask:0x1
	v_fmac_f32_dpp v148, v114, v200 row_ror:1 row_mask:0xf bank_mask:0x1
	v_fmac_f32_dpp v149, v115, v201 row_ror:1 row_mask:0xf bank_mask:0x1
	v_fmac_f32_dpp v254, v112, v182 row_ror:2 row_mask:0xf bank_mask:0x1
	v_fmac_f32_dpp v255, v113, v183 row_ror:2 row_mask:0xf bank_mask:0x1
	v_fmac_f32_dpp v148, v114, v184 row_ror:2 row_mask:0xf bank_mask:0x1
	v_fmac_f32_dpp v149, v115, v185 row_ror:2 row_mask:0xf bank_mask:0x1
	v_pk_mul_f32 v[254:255], v[238:239], v[254:255]
	v_pk_mul_f32 v[148:149], v[240:241], v[148:149]
	v_cvt_pk_bf16_f32 v244, v254, v255
	v_cvt_pk_bf16_f32 v245, v148, v149
	s_add_u32 s56, s46, 0x2c000
	s_addc_u32 s57, s47, 0
	global_store_dwordx4 v151, v[242:245], s[56:57]
	v_mov_b32_e32 v220, 0
	v_mov_b32_e32 v221, 0
	v_mov_b32_e32 v222, 0
	v_mov_b32_e32 v223, 0
	s_and_b32 s14, s75, 31
	s_cselect_b64 s[92:93], -1, 0
	s_and_b64 vcc, exec, s[86:87]
	s_cbranch_vccnz .Lfe_h0a
	s_and_b64 vcc, exec, s[92:93]
	s_cbranch_vccz .Lfe_h0a
	s_mov_b64 s[14:15], exec
	s_mov_b64 exec, s[10:11]
	global_load_dwordx4 v[220:223], v150, s[44:45]
	global_load_dwordx4 v[224:227], v150, s[44:45] offset:16
	global_load_dwordx4 v[228:231], v150, s[44:45] offset:512
	global_load_dwordx4 v[232:235], v150, s[44:45] offset:528
	s_mov_b64 exec, s[14:15]

; __global__ void __launch_bounds__(512, 2) fwd_kernel(Args a) {
;     ...
;         for (int m = MP + gw; m < MTOT; m += NGW) {
;             f32x4* xr4 = (f32x4*)(out + (size_t)m * D) + lane;
;             f32x4 v[4]; float sq = 0.f;
; #pragma unroll
;             for (int j = 0; j < 4; ++j) { v[j] = xr4[64 * j]; sq += (v[j][0] * v[j][0] + v[j][1] * v[j][1]) + (v[j][2] * v[j][2] + v[j][3] * v[j][3]); }
;             const float rstd = rsqrtf(wave_sum(sq) * (1.0f / D) + EPS);
; #pragma unroll
;             for (int j = 0; j < 4; ++j) { const f32x4 gq = ((const f32x4*)g_fin)[lane + 64 * j]; xr4[64 * j] = v[j] * rstd * gq; }
;         }
.LBB0_1180:
	global_load_dwordx4 v[12:15], v[2:3], off offset:-2048
	global_load_dwordx4 v[16:19], v[2:3], off offset:-1024
	global_load_dwordx4 v[20:23], v[2:3], off offset:1024
	global_load_dwordx4 v[24:27], v[2:3], off
	global_load_dwordx4 v[28:31], v[0:1], off
	global_load_dwordx4 v[48:51], v[0:1], off offset:1024
	global_load_dwordx4 v[52:55], v[0:1], off offset:2048
	global_load_dwordx4 v[56:59], v[0:1], off offset:3072
	s_add_i32 s4, s4, s30
	s_cmpk_gt_i32 s4, 0x407f
	s_waitcnt vmcnt(7)
	v_pk_mul_f32 v[32:33], v[14:15], v[14:15]
	v_pk_mul_f32 v[34:35], v[12:13], v[12:13]
	s_waitcnt vmcnt(6)
	v_pk_mul_f32 v[36:37], v[18:19], v[18:19]
	v_pk_mul_f32 v[38:39], v[16:17], v[16:17]
	v_pk_mov_b32 v[44:45], v[34:35], v[32:33] op_sel:[1,0]
	v_mov_b32_e32 v35, v33
	v_pk_mov_b32 v[32:33], v[38:39], v[36:37] op_sel:[1,0]
	v_mov_b32_e32 v39, v37
	s_waitcnt vmcnt(5)
	v_mul_f32_e32 v43, v21, v21
	s_waitcnt vmcnt(4)
	v_mul_f32_e32 v40, v25, v25
	v_mul_f32_e32 v42, v27, v27
	v_pk_add_f32 v[34:35], v[44:45], v[34:35]
	v_pk_add_f32 v[32:33], v[32:33], v[38:39]
	v_mul_f32_e32 v11, v20, v20
	v_mul_f32_e32 v46, v22, v22
	v_mul_f32_e32 v47, v23, v23
	v_pk_fma_f32 v[36:37], v[24:25], v[24:25], v[40:41] op_sel_hi:[1,1,0]
	v_pk_fma_f32 v[40:41], v[26:27], v[26:27], v[42:43] op_sel_hi:[1,1,0]
	v_pk_add_f32 v[34:35], v[34:35], v[34:35] op_sel:[0,1] op_sel_hi:[1,0]
	v_pk_add_f32 v[32:33], v[32:33], v[32:33] op_sel:[0,1] op_sel_hi:[1,0]
	v_mov_b32_e32 v37, v46
	v_mov_b32_e32 v41, v47
	v_mov_b32_e32 v35, v11
	v_mov_b32_e32 v33, v43
	v_pk_add_f32 v[36:37], v[36:37], v[40:41]
	v_pk_add_f32 v[32:33], v[34:35], v[32:33]
	s_nop 0
	v_pk_add_f32 v[32:33], v[32:33], v[36:37]
	s_nop 0
	v_add_f32_e32 v11, v32, v33
	ds_bpermute_b32 v32, v4, v11
	s_waitcnt lgkmcnt(0)
	v_add_f32_e32 v11, v11, v32
	ds_bpermute_b32 v32, v5, v11
	s_waitcnt lgkmcnt(0)
	v_add_f32_e32 v11, v11, v32
	ds_bpermute_b32 v32, v6, v11
	s_waitcnt lgkmcnt(0)
	v_add_f32_e32 v11, v11, v32
	ds_bpermute_b32 v32, v7, v11
	s_waitcnt lgkmcnt(0)
	v_add_f32_e32 v11, v11, v32
	ds_bpermute_b32 v32, v8, v11
	s_waitcnt lgkmcnt(0)
	v_add_f32_e32 v11, v11, v32
	ds_bpermute_b32 v32, v9, v11
	s_waitcnt lgkmcnt(0)
	v_add_f32_e32 v11, v11, v32
	v_fmamk_f32 v11, v11, 0x3a800000, v10
	v_mul_f32_e32 v32, 0x4b800000, v11
	v_cmp_gt_f32_e32 vcc, s0, v11
	s_nop 1
	v_cndmask_b32_e32 v11, v11, v32, vcc
	v_rsq_f32_e32 v11, v11
	s_nop 0
	v_mul_f32_e32 v32, 0x45800000, v11
	v_cndmask_b32_e32 v32, v11, v32, vcc
	v_pk_mul_f32 v[12:13], v[32:33], v[12:13] op_sel_hi:[0,1]
	v_pk_mul_f32 v[14:15], v[32:33], v[14:15] op_sel_hi:[0,1]
	s_waitcnt vmcnt(3)
	v_pk_mul_f32 v[14:15], v[30:31], v[14:15]
	v_pk_mul_f32 v[12:13], v[28:29], v[12:13]
	global_store_dwordx4 v[2:3], v[12:15], off offset:-2048
	v_pk_mul_f32 v[18:19], v[32:33], v[18:19] op_sel_hi:[0,1]
	v_pk_mul_f32 v[16:17], v[32:33], v[16:17] op_sel_hi:[0,1]
	s_waitcnt vmcnt(3)
	v_pk_mul_f32 v[12:13], v[48:49], v[16:17]
	v_pk_mul_f32 v[14:15], v[50:51], v[18:19]
	global_store_dwordx4 v[2:3], v[12:15], off offset:-1024
	v_pk_mul_f32 v[16:17], v[32:33], v[26:27] op_sel_hi:[0,1]
	v_pk_mul_f32 v[18:19], v[32:33], v[24:25] op_sel_hi:[0,1]
	s_waitcnt vmcnt(3)
	v_pk_mul_f32 v[12:13], v[52:53], v[18:19]
	v_pk_mul_f32 v[14:15], v[54:55], v[16:17]
	global_store_dwordx4 v[2:3], v[12:15], off
	v_pk_mul_f32 v[16:17], v[32:33], v[22:23] op_sel_hi:[0,1]
	v_pk_mul_f32 v[18:19], v[32:33], v[20:21] op_sel_hi:[0,1]
	s_waitcnt vmcnt(3)
	v_pk_mul_f32 v[12:13], v[56:57], v[18:19]
	v_pk_mul_f32 v[14:15], v[58:59], v[16:17]
	global_store_dwordx4 v[2:3], v[12:15], off offset:1024
	v_lshl_add_u64 v[2:3], v[2:3], 0, s[8:9]
	s_cbranch_scc0 .LBB0_1180
